# hyena main loop: next diagonal's LDS fragment reads interleaved into the 16-MFMA burst (3 per MFMA gap) instead of issued ahead of it; rest as v45
# speedup vs baseline: 1.0100x; 1.0030x over previous
; __device__ __forceinline__ void phase_hyena(int l, LAS unsigned char* lds, int G) {
;     ...
;         { int D = Dlo;
;           for (; D < 8 * wave - 59; ++D) HY_BODY(true, false);
;           for (; D <= 8 * wave + 3; ++D) HY_BODY(true, true);
;           for (; D <= Dhi; ++D) HY_BODY(false, true); }
.Lhy_x:
	s_waitcnt lgkmcnt(0)
	s_cmp_ge_i32 s2, s78
	s_cbranch_scc1 .Lhy_x_last
	s_setprio 1
	v_mfma_f32_32x32x16_bf16 v[48:63], v[10:13], v[92:95], v[48:63]
	v_add_u32_e32 v155, 0xffffff80, v155
	v_add_u32_e32 v15, -1, v15
	v_add_u32_e32 v14, 0xffffff80, v14
	v_mfma_f32_32x32x16_bf16 v[64:79], v[10:13], v[108:111], v[64:79]
	v_add_u32_e32 v0, 0xffffff80, v0
	s_add_i32 s2, s2, 1
	v_mov_b64_e32 v[176:177], v[80:81]
	v_mfma_f32_32x32x16_bf16 v[16:31], v[80:83], v[92:95], v[16:31]
	v_mov_b64_e32 v[178:179], v[82:83]
	v_mov_b64_e32 v[180:181], v[6:7]
	v_mov_b64_e32 v[182:183], v[8:9]
	v_mfma_f32_32x32x16_bf16 v[32:47], v[80:83], v[108:111], v[32:47]
	v_add_u32_e32 v156, v155, v128
	v_add_u32_e32 v156, 0x12040, v156
	ds_read2_b32 v[160:161], v156 offset0:0 offset1:1
	v_mfma_f32_32x32x16_bf16 v[48:63], v[2:5], v[100:103], v[48:63]
	ds_read2_b32 v[162:163], v156 offset0:2 offset1:3
	ds_read2_b32 v[164:165], v156 offset0:8 offset1:9
	ds_read2_b32 v[166:167], v156 offset0:10 offset1:11
	v_mfma_f32_32x32x16_bf16 v[64:79], v[2:5], v[116:119], v[64:79]
	ds_read2_b32 v[168:169], v156 offset0:16 offset1:17
	ds_read2_b32 v[170:171], v156 offset0:18 offset1:19
	ds_read2_b32 v[172:173], v156 offset0:24 offset1:25
	v_mfma_f32_32x32x16_bf16 v[16:31], v[6:9], v[100:103], v[16:31]
	ds_read2_b32 v[174:175], v156 offset0:26 offset1:27
	v_cmp_gt_u32_e32 vcc, 64, v15
	v_add_u32_e32 v157, v14, v128
	v_mfma_f32_32x32x16_bf16 v[32:47], v[6:9], v[116:119], v[32:47]
	v_add_u32_e32 v159, 4, v15
	v_cndmask_b32_e32 v157, v227, v157, vcc
	ds_read_b128 v[184:187], v157
	v_mfma_f32_32x32x16_bf16 v[48:63], v[88:91], v[96:99], v[48:63]
	ds_read_b128 v[204:207], v157 offset:32
	ds_read_b128 v[208:211], v157 offset:64
	ds_read_b128 v[212:215], v157 offset:96
	v_mfma_f32_32x32x16_bf16 v[64:79], v[88:91], v[112:115], v[64:79]
	v_cmp_gt_u32_e32 vcc, 64, v159
	v_add_u32_e32 v158, v0, v128
	s_nop 0
	v_mfma_f32_32x32x16_bf16 v[16:31], v[10:13], v[96:99], v[16:31]
	v_cndmask_b32_e32 v158, v227, v158, vcc
	ds_read_b128 v[228:231], v158
	ds_read_b128 v[232:235], v158 offset:32
	v_mfma_f32_32x32x16_bf16 v[32:47], v[10:13], v[112:115], v[32:47]
	ds_read_b128 v[236:239], v158 offset:64
	ds_read_b128 v[240:243], v158 offset:96
	v_mfma_f32_32x32x16_bf16 v[48:63], v[84:87], v[104:107], v[48:63]
	v_mfma_f32_32x32x16_bf16 v[64:79], v[84:87], v[120:123], v[64:79]
	v_mfma_f32_32x32x16_bf16 v[16:31], v[2:5], v[104:107], v[16:31]
	v_mfma_f32_32x32x16_bf16 v[32:47], v[2:5], v[120:123], v[32:47]
	s_setprio 0
	s_waitcnt lgkmcnt(0)
	s_cmp_ge_i32 s2, s78
	s_cbranch_scc1 .Lhy_y_last
	s_setprio 1
	v_mfma_f32_32x32x16_bf16 v[48:63], v[168:171], v[184:187], v[48:63]
	v_add_u32_e32 v155, 0xffffff80, v155
	v_add_u32_e32 v15, -1, v15
	v_add_u32_e32 v14, 0xffffff80, v14
	v_mfma_f32_32x32x16_bf16 v[64:79], v[168:171], v[228:231], v[64:79]
	v_add_u32_e32 v0, 0xffffff80, v0
	s_add_i32 s2, s2, 1
	v_mov_b64_e32 v[88:89], v[160:161]
	v_mfma_f32_32x32x16_bf16 v[16:31], v[160:163], v[184:187], v[16:31]
	v_mov_b64_e32 v[90:91], v[162:163]
	v_mov_b64_e32 v[84:85], v[164:165]
	v_mov_b64_e32 v[86:87], v[166:167]
	v_mfma_f32_32x32x16_bf16 v[32:47], v[160:163], v[228:231], v[32:47]
	v_add_u32_e32 v156, v155, v128
	v_add_u32_e32 v156, 0x12040, v156
	ds_read2_b32 v[80:81], v156 offset0:0 offset1:1
	v_mfma_f32_32x32x16_bf16 v[48:63], v[172:175], v[204:207], v[48:63]
	ds_read2_b32 v[82:83], v156 offset0:2 offset1:3
	ds_read2_b32 v[6:7], v156 offset0:8 offset1:9
	ds_read2_b32 v[8:9], v156 offset0:10 offset1:11
	v_mfma_f32_32x32x16_bf16 v[64:79], v[172:175], v[232:235], v[64:79]
	ds_read2_b32 v[10:11], v156 offset0:16 offset1:17
	ds_read2_b32 v[12:13], v156 offset0:18 offset1:19
	ds_read2_b32 v[2:3], v156 offset0:24 offset1:25
	v_mfma_f32_32x32x16_bf16 v[16:31], v[164:167], v[204:207], v[16:31]
	ds_read2_b32 v[4:5], v156 offset0:26 offset1:27
	v_cmp_gt_u32_e32 vcc, 64, v15
	v_add_u32_e32 v157, v14, v128
	v_mfma_f32_32x32x16_bf16 v[32:47], v[164:167], v[232:235], v[32:47]
	v_add_u32_e32 v159, 4, v15
	v_cndmask_b32_e32 v157, v227, v157, vcc
	ds_read_b128 v[92:95], v157
	v_mfma_f32_32x32x16_bf16 v[48:63], v[176:179], v[208:211], v[48:63]
	ds_read_b128 v[100:103], v157 offset:32
	ds_read_b128 v[96:99], v157 offset:64
	ds_read_b128 v[104:107], v157 offset:96
	v_mfma_f32_32x32x16_bf16 v[64:79], v[176:179], v[236:239], v[64:79]
	v_cmp_gt_u32_e32 vcc, 64, v159
	v_add_u32_e32 v158, v0, v128
	s_nop 0
	v_mfma_f32_32x32x16_bf16 v[16:31], v[168:171], v[208:211], v[16:31]
	v_cndmask_b32_e32 v158, v227, v158, vcc
	ds_read_b128 v[108:111], v158
	ds_read_b128 v[116:119], v158 offset:32
	v_mfma_f32_32x32x16_bf16 v[32:47], v[168:171], v[236:239], v[32:47]
	ds_read_b128 v[112:115], v158 offset:64
	ds_read_b128 v[120:123], v158 offset:96
	v_mfma_f32_32x32x16_bf16 v[48:63], v[180:183], v[212:215], v[48:63]
	v_mfma_f32_32x32x16_bf16 v[64:79], v[180:183], v[240:243], v[64:79]
	v_mfma_f32_32x32x16_bf16 v[16:31], v[172:175], v[212:215], v[16:31]
	v_mfma_f32_32x32x16_bf16 v[32:47], v[172:175], v[240:243], v[32:47]
	s_setprio 0
	s_branch .Lhy_x
